# conversion-queue FFN tiles converted by the scan loader waves only during the 16-step prompt segments (not in the short sample segments)
# baseline (speedup 1.0000x reference)
.Lcv_b_done:
	s_mov_b32 s94, 0
	s_cmp_eq_u32 s95, 2
	s_cbranch_scc1 .Lcv_drain_ret
	s_cmp_lg_u32 s95, 0
	s_cbranch_scc1 .Lcv_pad10
	s_cmp_ge_i32 s57, s38
	s_cbranch_scc1 .Lcv_pad10
